# P4 unit boundary: one workgroup barrier (behind the ticket write) instead of two
# baseline (speedup 1.0000x reference)
.LBB0_556:
	s_cmp_lg_u32 s84, -1
	s_cselect_b32 s0, s84, 0
	s_cselect_b32 s1, s85, 0
	v_mov_b32_e32 v4, s0
	v_mov_b32_e32 v5, s1
	v_mov_b32_e32 v4, 0x24240
	ds_read_b32 v3, v4
	s_mov_b64 s[0:1], -1
	s_waitcnt lgkmcnt(0)
	v_readfirstlane_b32 s4, v3
	s_cmpk_gt_i32 s4, 0x5ff
	s_cbranch_scc1 .LBB0_555
	v_readlane_b32 s0, v243, 11
	v_mov_b32_e32 v192, v0
	v_readlane_b32 s1, v243, 12
	s_cmpk_gt_i32 s4, 0x1ff
	v_readfirstlane_b32 s25, v192
	s_nop 2
	global_load_dword v18, v2, s[0:1]
	s_cselect_b64 s[0:1], -1, 0
	s_add_i32 s5, s4, 0xfffffe00
	s_cmpk_lt_i32 s4, 0x200
	v_writelane_b32 v243, s0, 43
	s_cselect_b64 s[2:3], -1, 0
	v_cndmask_b32_e64 v3, 0, 1, s[2:3]
	v_writelane_b32 v243, s1, 44
	s_and_b64 s[0:1], s[2:3], exec
	s_cselect_b32 s6, s4, s5
	s_movk_i32 s0, 0x1d0
	s_and_b32 s26, s6, 1
	v_cmp_gt_i32_e32 vcc, s0, v192
	v_cmp_ne_u32_e64 s[4:5], 1, v3
	s_and_saveexec_b64 s[0:1], vcc
	s_cbranch_execz .Ltp_a
	s_and_b64 s[8:9], s[2:3], exec
	s_cselect_b32 s7, 8, 0
	s_lshl_b32 s8, s26, 2
	s_or_b32 s7, s8, s7
	s_mulk_i32 s7, 0x740
	v_readlane_b32 s8, v243, 9
	v_readlane_b32 s9, v243, 10
	s_add_u32 s8, s8, s7
	v_lshlrev_b32_e32 v4, 2, v192
	s_addc_u32 s9, s9, 0
	v_ashrrev_i32_e32 v5, 31, v4
	v_lshl_add_u64 v[6:7], v[4:5], 2, s[8:9]
	global_load_dwordx4 v[6:9], v[6:7], off
	s_and_b64 vcc, exec, s[4:5]
	s_cbranch_vccnz .Ltp_a
	s_mul_i32 s7, s26, 0x1d00
	v_readlane_b32 s8, v243, 9
	v_readlane_b32 s9, v243, 10
	s_add_u32 s8, s8, s7
	s_addc_u32 s9, s9, 0
	v_lshl_add_u64 v[10:11], v[4:5], 2, s[8:9]
	v_add_co_u32_e32 v10, vcc, 0x7000, v10
	s_nop 1
	v_addc_co_u32_e32 v11, vcc, 0, v11, vcc
	global_load_dwordx4 v[10:13], v[10:11], off offset:1024
